# srcC=0 first K-tile + no zeroing MFMAs, no prefetch DMAs in a workgroup's final K-iteration, attn_combine vectorized to 16-byte accesses (4 heads per wave) with all loads batched
# speedup vs baseline: 1.0011x; 1.0011x over previous
.LBB0_328:
	s_waitcnt vmcnt(0) lgkmcnt(0)
	s_lshl_b32 s0, s23, 3
	s_add_i32 s0, s0, s20
	s_cmpk_gt_i32 s0, 0x7fff
	s_barrier
	s_cbranch_scc1 .LBB0_331
	s_lshl_b32 s1, s21, 3
	s_add_u32 s4, s12, 0x37e00000
	s_addc_u32 s5, s13, 0
	s_add_u32 s2, s12, 0x3de00000
	s_addc_u32 s3, s13, 0
	s_add_u32 s6, s12, 0x38e00000
	s_addc_u32 s7, s13, 0
	s_add_u32 s12, s12, 0x39e00000
	s_addc_u32 s13, s13, 0
	s_and_b32 s14, s20, 7
	s_lshl_b32 s56, s14, 7
	s_lshl_b32 s15, s14, 8
	v_lshlrev_b32_e32 v2, 1, v128
	s_add_u32 s10, s10, s15
	v_ashrrev_i32_e32 v3, 31, v2
	v_ashrrev_i32_e32 v129, 31, v128
	s_addc_u32 s11, s11, 0
	v_lshl_add_u64 v[2:3], v[2:3], 0, s[56:57]
	v_lshl_add_u64 v[4:5], v[128:129], 2, s[10:11]
	s_lshl_b32 s14, s14, 2
	s_cmpk_lg_u32 s1, 0x800
	s_cbranch_scc1 .LBB0_330
	s_sub_u32 s10, s10, s15
	s_subb_u32 s11, s11, 0
	s_and_b32 vcc_lo, s0, 1
	s_lshl_b32 vcc_hi, vcc_lo, 10
	s_lshl_b32 vcc_lo, vcc_lo, 4
	v_lshrrev_b32_e32 v2, 4, v128
	v_lshlrev_b32_e32 v2, 2, v2
	v_lshlrev_b32_e32 v4, 4, v128
	v_mov_b32_e32 v5, 0
	s_lshr_b32 s15, s0, 1
	s_add_u32 s15, s15, s22
	s_lshl_b32 s16, s15, 5
	s_add_u32 s16, s2, s16
	s_addc_u32 s17, s3, 0
	s_add_u32 s16, s16, vcc_lo
	s_addc_u32 s17, s17, 0
	global_load_dword v16, v2, s[16:17]
	s_add_u32 s16, s16, 0x40000
	s_addc_u32 s17, s17, 0
	global_load_dword v17, v2, s[16:17]
	s_add_u32 s16, s16, 0x40000
	s_addc_u32 s17, s17, 0
	global_load_dword v18, v2, s[16:17]
	s_lshl_b32 s16, s15, 11
	s_add_u32 s16, s4, s16
	s_addc_u32 s17, s5, 0
	s_add_u32 s16, s16, vcc_hi
	s_addc_u32 s17, s17, 0
	global_load_dwordx4 v[20:23], v4, s[16:17]
	s_lshl_b32 s16, s15, 11
	s_add_u32 s16, s6, s16
	s_addc_u32 s17, s7, 0
	s_add_u32 s16, s16, vcc_hi
	s_addc_u32 s17, s17, 0
	global_load_dwordx4 v[24:27], v4, s[16:17]
	s_lshl_b32 s16, s15, 11
	s_add_u32 s16, s12, s16
	s_addc_u32 s17, s13, 0
	s_add_u32 s16, s16, vcc_hi
	s_addc_u32 s17, s17, 0
	global_load_dwordx4 v[28:31], v4, s[16:17]
	s_lshl_b32 s16, s15, 12
	s_add_u32 s16, s10, s16
	s_addc_u32 s17, s11, 0
	s_add_u32 s16, s16, vcc_hi
	s_addc_u32 s17, s17, 0
	v_lshl_add_u64 v[32:33], s[16:17], 0, v[4:5]
	s_add_u32 s0, s0, s1
	s_lshr_b32 s15, s0, 1
	s_add_u32 s15, s15, s22
	s_lshl_b32 s16, s15, 5
	s_add_u32 s16, s2, s16
	s_addc_u32 s17, s3, 0
	s_add_u32 s16, s16, vcc_lo
	s_addc_u32 s17, s17, 0
	global_load_dword v36, v2, s[16:17]
	s_add_u32 s16, s16, 0x40000
	s_addc_u32 s17, s17, 0
	global_load_dword v37, v2, s[16:17]
	s_add_u32 s16, s16, 0x40000
	s_addc_u32 s17, s17, 0
	global_load_dword v38, v2, s[16:17]
	s_lshl_b32 s16, s15, 11
	s_add_u32 s16, s4, s16
	s_addc_u32 s17, s5, 0
	s_add_u32 s16, s16, vcc_hi
	s_addc_u32 s17, s17, 0
	global_load_dwordx4 v[40:43], v4, s[16:17]
	s_lshl_b32 s16, s15, 11
	s_add_u32 s16, s6, s16
	s_addc_u32 s17, s7, 0
	s_add_u32 s16, s16, vcc_hi
	s_addc_u32 s17, s17, 0
	global_load_dwordx4 v[44:47], v4, s[16:17]
	s_lshl_b32 s16, s15, 11
	s_add_u32 s16, s12, s16
	s_addc_u32 s17, s13, 0
	s_add_u32 s16, s16, vcc_hi
	s_addc_u32 s17, s17, 0
	global_load_dwordx4 v[48:51], v4, s[16:17]
	s_lshl_b32 s16, s15, 12
	s_add_u32 s16, s10, s16
	s_addc_u32 s17, s11, 0
	s_add_u32 s16, s16, vcc_hi
	s_addc_u32 s17, s17, 0
	v_lshl_add_u64 v[52:53], s[16:17], 0, v[4:5]
	s_add_u32 s0, s0, s1
	s_lshr_b32 s15, s0, 1
	s_add_u32 s15, s15, s22
	s_lshl_b32 s16, s15, 5
	s_add_u32 s16, s2, s16
	s_addc_u32 s17, s3, 0
	s_add_u32 s16, s16, vcc_lo
	s_addc_u32 s17, s17, 0
	global_load_dword v56, v2, s[16:17]
	s_add_u32 s16, s16, 0x40000
	s_addc_u32 s17, s17, 0
	global_load_dword v57, v2, s[16:17]
	s_add_u32 s16, s16, 0x40000
	s_addc_u32 s17, s17, 0
	global_load_dword v58, v2, s[16:17]
	s_lshl_b32 s16, s15, 11
	s_add_u32 s16, s4, s16
	s_addc_u32 s17, s5, 0
	s_add_u32 s16, s16, vcc_hi
	s_addc_u32 s17, s17, 0
	global_load_dwordx4 v[60:63], v4, s[16:17]
	s_lshl_b32 s16, s15, 11
	s_add_u32 s16, s6, s16
	s_addc_u32 s17, s7, 0
	s_add_u32 s16, s16, vcc_hi
	s_addc_u32 s17, s17, 0
	global_load_dwordx4 v[64:67], v4, s[16:17]
	s_lshl_b32 s16, s15, 11
	s_add_u32 s16, s12, s16
	s_addc_u32 s17, s13, 0
	s_add_u32 s16, s16, vcc_hi
	s_addc_u32 s17, s17, 0
	global_load_dwordx4 v[68:71], v4, s[16:17]
	s_lshl_b32 s16, s15, 12
	s_add_u32 s16, s10, s16
	s_addc_u32 s17, s11, 0
	s_add_u32 s16, s16, vcc_hi
	s_addc_u32 s17, s17, 0
	v_lshl_add_u64 v[72:73], s[16:17], 0, v[4:5]
	s_add_u32 s0, s0, s1
	s_lshr_b32 s15, s0, 1
	s_add_u32 s15, s15, s22
	s_lshl_b32 s16, s15, 5
	s_add_u32 s16, s2, s16
	s_addc_u32 s17, s3, 0
	s_add_u32 s16, s16, vcc_lo
	s_addc_u32 s17, s17, 0
	global_load_dword v76, v2, s[16:17]
	s_add_u32 s16, s16, 0x40000
	s_addc_u32 s17, s17, 0
	global_load_dword v77, v2, s[16:17]
	s_add_u32 s16, s16, 0x40000
	s_addc_u32 s17, s17, 0
	global_load_dword v78, v2, s[16:17]
	s_lshl_b32 s16, s15, 11
	s_add_u32 s16, s4, s16
	s_addc_u32 s17, s5, 0
	s_add_u32 s16, s16, vcc_hi
	s_addc_u32 s17, s17, 0
	global_load_dwordx4 v[80:83], v4, s[16:17]
	s_lshl_b32 s16, s15, 11
	s_add_u32 s16, s6, s16
	s_addc_u32 s17, s7, 0
	s_add_u32 s16, s16, vcc_hi
	s_addc_u32 s17, s17, 0
	global_load_dwordx4 v[84:87], v4, s[16:17]
	s_lshl_b32 s16, s15, 11
	s_add_u32 s16, s12, s16
	s_addc_u32 s17, s13, 0
	s_add_u32 s16, s16, vcc_hi
	s_addc_u32 s17, s17, 0
	global_load_dwordx4 v[88:91], v4, s[16:17]
	s_lshl_b32 s16, s15, 12
	s_add_u32 s16, s10, s16
	s_addc_u32 s17, s11, 0
	s_add_u32 s16, s16, vcc_hi
	s_addc_u32 s17, s17, 0
	v_lshl_add_u64 v[92:93], s[16:17], 0, v[4:5]
	s_add_u32 s0, s0, s1
	s_waitcnt vmcnt(18)
	v_max3_f32 v9, v16, v17, v18
	v_sub_f32_e32 v0, v16, v9
	v_exp_f32_e32 v6, v0
	v_sub_f32_e32 v0, v17, v9
	v_exp_f32_e32 v7, v0
	v_sub_f32_e32 v0, v18, v9
	v_exp_f32_e32 v8, v0
	v_add_f32_e32 v0, v6, v7
	v_add_f32_e32 v0, v8, v0
	v_div_scale_f32 v9, s[16:17], v0, v0, 1.0
	v_rcp_f32_e32 v10, v9
	s_nop 0
	v_fma_f32 v11, -v9, v10, 1.0
	v_fmac_f32_e32 v10, v11, v10
	v_div_scale_f32 v11, vcc, 1.0, v0, 1.0
	v_mul_f32_e32 v12, v11, v10
	v_fma_f32 v13, -v9, v12, v11
	v_fmac_f32_e32 v12, v13, v10
	v_fma_f32 v9, -v9, v12, v11
	v_div_fmas_f32 v9, v9, v10, v12
	v_div_fixup_f32 v0, v9, v0, 1.0
	v_mul_f32_e32 v6, v6, v0
	v_mul_f32_e32 v7, v7, v0
	v_mul_f32_e32 v8, v8, v0
	v_cvt_f32_f16_e32 v10, v24
	v_cvt_f32_f16_e32 v11, v20
	v_cvt_f32_f16_e32 v12, v28
	v_mul_f32_e32 v10, v7, v10
	v_fma_f32 v10, v6, v11, v10
	v_fma_f32 v10, v8, v12, v10
	v_cvt_f32_f16_sdwa v11, v20 dst_sel:DWORD dst_unused:UNUSED_PAD src0_sel:WORD_1
	v_cvt_f32_f16_sdwa v12, v24 dst_sel:DWORD dst_unused:UNUSED_PAD src0_sel:WORD_1
	v_cvt_f32_f16_sdwa v13, v28 dst_sel:DWORD dst_unused:UNUSED_PAD src0_sel:WORD_1
	v_mul_f32_e32 v11, v6, v11
	v_fma_f32 v11, v7, v12, v11
	v_fma_f32 v11, v8, v13, v11
	v_cvt_pk_bf16_f32 v20, v10, v11
	v_cvt_f32_f16_e32 v10, v25
	v_cvt_f32_f16_e32 v11, v21
	v_cvt_f32_f16_e32 v12, v29
	v_mul_f32_e32 v10, v7, v10
	v_fma_f32 v10, v6, v11, v10
	v_fma_f32 v10, v8, v12, v10
	v_cvt_f32_f16_sdwa v11, v21 dst_sel:DWORD dst_unused:UNUSED_PAD src0_sel:WORD_1
	v_cvt_f32_f16_sdwa v12, v25 dst_sel:DWORD dst_unused:UNUSED_PAD src0_sel:WORD_1
	v_cvt_f32_f16_sdwa v13, v29 dst_sel:DWORD dst_unused:UNUSED_PAD src0_sel:WORD_1
	v_mul_f32_e32 v11, v6, v11
	v_fma_f32 v11, v7, v12, v11
	v_fma_f32 v11, v8, v13, v11
	v_cvt_pk_bf16_f32 v21, v10, v11
	v_cvt_f32_f16_e32 v10, v26
	v_cvt_f32_f16_e32 v11, v22
	v_cvt_f32_f16_e32 v12, v30
	v_mul_f32_e32 v10, v7, v10
	v_fma_f32 v10, v6, v11, v10
	v_fma_f32 v10, v8, v12, v10
	v_cvt_f32_f16_sdwa v11, v22 dst_sel:DWORD dst_unused:UNUSED_PAD src0_sel:WORD_1
	v_cvt_f32_f16_sdwa v12, v26 dst_sel:DWORD dst_unused:UNUSED_PAD src0_sel:WORD_1
	v_cvt_f32_f16_sdwa v13, v30 dst_sel:DWORD dst_unused:UNUSED_PAD src0_sel:WORD_1
	v_mul_f32_e32 v11, v6, v11
	v_fma_f32 v11, v7, v12, v11
	v_fma_f32 v11, v8, v13, v11
	v_cvt_pk_bf16_f32 v22, v10, v11
	v_cvt_f32_f16_e32 v10, v27
	v_cvt_f32_f16_e32 v11, v23
	v_cvt_f32_f16_e32 v12, v31
	v_mul_f32_e32 v10, v7, v10
	v_fma_f32 v10, v6, v11, v10
	v_fma_f32 v10, v8, v12, v10
	v_cvt_f32_f16_sdwa v11, v23 dst_sel:DWORD dst_unused:UNUSED_PAD src0_sel:WORD_1
	v_cvt_f32_f16_sdwa v12, v27 dst_sel:DWORD dst_unused:UNUSED_PAD src0_sel:WORD_1
	v_cvt_f32_f16_sdwa v13, v31 dst_sel:DWORD dst_unused:UNUSED_PAD src0_sel:WORD_1
	v_mul_f32_e32 v11, v6, v11
	v_fma_f32 v11, v7, v12, v11
	v_fma_f32 v11, v8, v13, v11
	v_cvt_pk_bf16_f32 v23, v10, v11
	global_store_dwordx4 v[32:33], v[20:23], off
	s_waitcnt vmcnt(13)
	v_max3_f32 v9, v36, v37, v38
	v_sub_f32_e32 v0, v36, v9
	v_exp_f32_e32 v6, v0
	v_sub_f32_e32 v0, v37, v9
	v_exp_f32_e32 v7, v0
	v_sub_f32_e32 v0, v38, v9
	v_exp_f32_e32 v8, v0
	v_add_f32_e32 v0, v6, v7
	v_add_f32_e32 v0, v8, v0
	v_div_scale_f32 v9, s[16:17], v0, v0, 1.0
	v_rcp_f32_e32 v10, v9
	s_nop 0
	v_fma_f32 v11, -v9, v10, 1.0
	v_fmac_f32_e32 v10, v11, v10
	v_div_scale_f32 v11, vcc, 1.0, v0, 1.0
	v_mul_f32_e32 v12, v11, v10
	v_fma_f32 v13, -v9, v12, v11
	v_fmac_f32_e32 v12, v13, v10
	v_fma_f32 v9, -v9, v12, v11
	v_div_fmas_f32 v9, v9, v10, v12
	v_div_fixup_f32 v0, v9, v0, 1.0
	v_mul_f32_e32 v6, v6, v0
	v_mul_f32_e32 v7, v7, v0
	v_mul_f32_e32 v8, v8, v0
	v_cvt_f32_f16_e32 v10, v44
	v_cvt_f32_f16_e32 v11, v40
	v_cvt_f32_f16_e32 v12, v48
	v_mul_f32_e32 v10, v7, v10
	v_fma_f32 v10, v6, v11, v10
	v_fma_f32 v10, v8, v12, v10
	v_cvt_f32_f16_sdwa v11, v40 dst_sel:DWORD dst_unused:UNUSED_PAD src0_sel:WORD_1
	v_cvt_f32_f16_sdwa v12, v44 dst_sel:DWORD dst_unused:UNUSED_PAD src0_sel:WORD_1
	v_cvt_f32_f16_sdwa v13, v48 dst_sel:DWORD dst_unused:UNUSED_PAD src0_sel:WORD_1
	v_mul_f32_e32 v11, v6, v11
	v_fma_f32 v11, v7, v12, v11
	v_fma_f32 v11, v8, v13, v11
	v_cvt_pk_bf16_f32 v40, v10, v11
	v_cvt_f32_f16_e32 v10, v45
	v_cvt_f32_f16_e32 v11, v41
	v_cvt_f32_f16_e32 v12, v49
	v_mul_f32_e32 v10, v7, v10
	v_fma_f32 v10, v6, v11, v10
	v_fma_f32 v10, v8, v12, v10
	v_cvt_f32_f16_sdwa v11, v41 dst_sel:DWORD dst_unused:UNUSED_PAD src0_sel:WORD_1
	v_cvt_f32_f16_sdwa v12, v45 dst_sel:DWORD dst_unused:UNUSED_PAD src0_sel:WORD_1
	v_cvt_f32_f16_sdwa v13, v49 dst_sel:DWORD dst_unused:UNUSED_PAD src0_sel:WORD_1
	v_mul_f32_e32 v11, v6, v11
	v_fma_f32 v11, v7, v12, v11
	v_fma_f32 v11, v8, v13, v11
	v_cvt_pk_bf16_f32 v41, v10, v11
	v_cvt_f32_f16_e32 v10, v46
	v_cvt_f32_f16_e32 v11, v42
	v_cvt_f32_f16_e32 v12, v50
	v_mul_f32_e32 v10, v7, v10
	v_fma_f32 v10, v6, v11, v10
	v_fma_f32 v10, v8, v12, v10
	v_cvt_f32_f16_sdwa v11, v42 dst_sel:DWORD dst_unused:UNUSED_PAD src0_sel:WORD_1
	v_cvt_f32_f16_sdwa v12, v46 dst_sel:DWORD dst_unused:UNUSED_PAD src0_sel:WORD_1
	v_cvt_f32_f16_sdwa v13, v50 dst_sel:DWORD dst_unused:UNUSED_PAD src0_sel:WORD_1
	v_mul_f32_e32 v11, v6, v11
	v_fma_f32 v11, v7, v12, v11
	v_fma_f32 v11, v8, v13, v11
	v_cvt_pk_bf16_f32 v42, v10, v11
	v_cvt_f32_f16_e32 v10, v47
	v_cvt_f32_f16_e32 v11, v43
	v_cvt_f32_f16_e32 v12, v51
	v_mul_f32_e32 v10, v7, v10
	v_fma_f32 v10, v6, v11, v10
	v_fma_f32 v10, v8, v12, v10
	v_cvt_f32_f16_sdwa v11, v43 dst_sel:DWORD dst_unused:UNUSED_PAD src0_sel:WORD_1
	v_cvt_f32_f16_sdwa v12, v47 dst_sel:DWORD dst_unused:UNUSED_PAD src0_sel:WORD_1
	v_cvt_f32_f16_sdwa v13, v51 dst_sel:DWORD dst_unused:UNUSED_PAD src0_sel:WORD_1
	v_mul_f32_e32 v11, v6, v11
	v_fma_f32 v11, v7, v12, v11
	v_fma_f32 v11, v8, v13, v11
	v_cvt_pk_bf16_f32 v43, v10, v11
	global_store_dwordx4 v[52:53], v[40:43], off
	s_waitcnt vmcnt(8)
	v_max3_f32 v9, v56, v57, v58
	v_sub_f32_e32 v0, v56, v9
	v_exp_f32_e32 v6, v0
	v_sub_f32_e32 v0, v57, v9
	v_exp_f32_e32 v7, v0
	v_sub_f32_e32 v0, v58, v9
	v_exp_f32_e32 v8, v0
	v_add_f32_e32 v0, v6, v7
	v_add_f32_e32 v0, v8, v0
	v_div_scale_f32 v9, s[16:17], v0, v0, 1.0
	v_rcp_f32_e32 v10, v9
	s_nop 0
	v_fma_f32 v11, -v9, v10, 1.0
	v_fmac_f32_e32 v10, v11, v10
	v_div_scale_f32 v11, vcc, 1.0, v0, 1.0
	v_mul_f32_e32 v12, v11, v10
	v_fma_f32 v13, -v9, v12, v11
	v_fmac_f32_e32 v12, v13, v10
	v_fma_f32 v9, -v9, v12, v11
	v_div_fmas_f32 v9, v9, v10, v12
	v_div_fixup_f32 v0, v9, v0, 1.0
	v_mul_f32_e32 v6, v6, v0
	v_mul_f32_e32 v7, v7, v0
	v_mul_f32_e32 v8, v8, v0
	v_cvt_f32_f16_e32 v10, v64
	v_cvt_f32_f16_e32 v11, v60
	v_cvt_f32_f16_e32 v12, v68
	v_mul_f32_e32 v10, v7, v10
	v_fma_f32 v10, v6, v11, v10
	v_fma_f32 v10, v8, v12, v10
	v_cvt_f32_f16_sdwa v11, v60 dst_sel:DWORD dst_unused:UNUSED_PAD src0_sel:WORD_1
	v_cvt_f32_f16_sdwa v12, v64 dst_sel:DWORD dst_unused:UNUSED_PAD src0_sel:WORD_1
	v_cvt_f32_f16_sdwa v13, v68 dst_sel:DWORD dst_unused:UNUSED_PAD src0_sel:WORD_1
	v_mul_f32_e32 v11, v6, v11
	v_fma_f32 v11, v7, v12, v11
	v_fma_f32 v11, v8, v13, v11
	v_cvt_pk_bf16_f32 v60, v10, v11
	v_cvt_f32_f16_e32 v10, v65
	v_cvt_f32_f16_e32 v11, v61
	v_cvt_f32_f16_e32 v12, v69
	v_mul_f32_e32 v10, v7, v10
	v_fma_f32 v10, v6, v11, v10
	v_fma_f32 v10, v8, v12, v10
	v_cvt_f32_f16_sdwa v11, v61 dst_sel:DWORD dst_unused:UNUSED_PAD src0_sel:WORD_1
	v_cvt_f32_f16_sdwa v12, v65 dst_sel:DWORD dst_unused:UNUSED_PAD src0_sel:WORD_1
	v_cvt_f32_f16_sdwa v13, v69 dst_sel:DWORD dst_unused:UNUSED_PAD src0_sel:WORD_1
	v_mul_f32_e32 v11, v6, v11
	v_fma_f32 v11, v7, v12, v11
	v_fma_f32 v11, v8, v13, v11
	v_cvt_pk_bf16_f32 v61, v10, v11
	v_cvt_f32_f16_e32 v10, v66
	v_cvt_f32_f16_e32 v11, v62
	v_cvt_f32_f16_e32 v12, v70
	v_mul_f32_e32 v10, v7, v10
	v_fma_f32 v10, v6, v11, v10
	v_fma_f32 v10, v8, v12, v10
	v_cvt_f32_f16_sdwa v11, v62 dst_sel:DWORD dst_unused:UNUSED_PAD src0_sel:WORD_1
	v_cvt_f32_f16_sdwa v12, v66 dst_sel:DWORD dst_unused:UNUSED_PAD src0_sel:WORD_1
	v_cvt_f32_f16_sdwa v13, v70 dst_sel:DWORD dst_unused:UNUSED_PAD src0_sel:WORD_1
	v_mul_f32_e32 v11, v6, v11
	v_fma_f32 v11, v7, v12, v11
	v_fma_f32 v11, v8, v13, v11
	v_cvt_pk_bf16_f32 v62, v10, v11
	v_cvt_f32_f16_e32 v10, v67
	v_cvt_f32_f16_e32 v11, v63
	v_cvt_f32_f16_e32 v12, v71
	v_mul_f32_e32 v10, v7, v10
	v_fma_f32 v10, v6, v11, v10
	v_fma_f32 v10, v8, v12, v10
	v_cvt_f32_f16_sdwa v11, v63 dst_sel:DWORD dst_unused:UNUSED_PAD src0_sel:WORD_1
	v_cvt_f32_f16_sdwa v12, v67 dst_sel:DWORD dst_unused:UNUSED_PAD src0_sel:WORD_1
	v_cvt_f32_f16_sdwa v13, v71 dst_sel:DWORD dst_unused:UNUSED_PAD src0_sel:WORD_1
	v_mul_f32_e32 v11, v6, v11
	v_fma_f32 v11, v7, v12, v11
	v_fma_f32 v11, v8, v13, v11
	v_cvt_pk_bf16_f32 v63, v10, v11
	global_store_dwordx4 v[72:73], v[60:63], off
	s_waitcnt vmcnt(3)
	v_max3_f32 v9, v76, v77, v78
	v_sub_f32_e32 v0, v76, v9
	v_exp_f32_e32 v6, v0
	v_sub_f32_e32 v0, v77, v9
	v_exp_f32_e32 v7, v0
	v_sub_f32_e32 v0, v78, v9
	v_exp_f32_e32 v8, v0
	v_add_f32_e32 v0, v6, v7
	v_add_f32_e32 v0, v8, v0
	v_div_scale_f32 v9, s[16:17], v0, v0, 1.0
	v_rcp_f32_e32 v10, v9
	s_nop 0
	v_fma_f32 v11, -v9, v10, 1.0
	v_fmac_f32_e32 v10, v11, v10
	v_div_scale_f32 v11, vcc, 1.0, v0, 1.0
	v_mul_f32_e32 v12, v11, v10
	v_fma_f32 v13, -v9, v12, v11
	v_fmac_f32_e32 v12, v13, v10
	v_fma_f32 v9, -v9, v12, v11
	v_div_fmas_f32 v9, v9, v10, v12
	v_div_fixup_f32 v0, v9, v0, 1.0
	v_mul_f32_e32 v6, v6, v0
	v_mul_f32_e32 v7, v7, v0
	v_mul_f32_e32 v8, v8, v0
	v_cvt_f32_f16_e32 v10, v84
	v_cvt_f32_f16_e32 v11, v80
	v_cvt_f32_f16_e32 v12, v88
	v_mul_f32_e32 v10, v7, v10
	v_fma_f32 v10, v6, v11, v10
	v_fma_f32 v10, v8, v12, v10
	v_cvt_f32_f16_sdwa v11, v80 dst_sel:DWORD dst_unused:UNUSED_PAD src0_sel:WORD_1
	v_cvt_f32_f16_sdwa v12, v84 dst_sel:DWORD dst_unused:UNUSED_PAD src0_sel:WORD_1
	v_cvt_f32_f16_sdwa v13, v88 dst_sel:DWORD dst_unused:UNUSED_PAD src0_sel:WORD_1
	v_mul_f32_e32 v11, v6, v11
	v_fma_f32 v11, v7, v12, v11
	v_fma_f32 v11, v8, v13, v11
	v_cvt_pk_bf16_f32 v80, v10, v11
	v_cvt_f32_f16_e32 v10, v85
	v_cvt_f32_f16_e32 v11, v81
	v_cvt_f32_f16_e32 v12, v89
	v_mul_f32_e32 v10, v7, v10
	v_fma_f32 v10, v6, v11, v10
	v_fma_f32 v10, v8, v12, v10
	v_cvt_f32_f16_sdwa v11, v81 dst_sel:DWORD dst_unused:UNUSED_PAD src0_sel:WORD_1
	v_cvt_f32_f16_sdwa v12, v85 dst_sel:DWORD dst_unused:UNUSED_PAD src0_sel:WORD_1
	v_cvt_f32_f16_sdwa v13, v89 dst_sel:DWORD dst_unused:UNUSED_PAD src0_sel:WORD_1
	v_mul_f32_e32 v11, v6, v11
	v_fma_f32 v11, v7, v12, v11
	v_fma_f32 v11, v8, v13, v11
	v_cvt_pk_bf16_f32 v81, v10, v11
	v_cvt_f32_f16_e32 v10, v86
	v_cvt_f32_f16_e32 v11, v82
	v_cvt_f32_f16_e32 v12, v90
	v_mul_f32_e32 v10, v7, v10
	v_fma_f32 v10, v6, v11, v10
	v_fma_f32 v10, v8, v12, v10
	v_cvt_f32_f16_sdwa v11, v82 dst_sel:DWORD dst_unused:UNUSED_PAD src0_sel:WORD_1
	v_cvt_f32_f16_sdwa v12, v86 dst_sel:DWORD dst_unused:UNUSED_PAD src0_sel:WORD_1
	v_cvt_f32_f16_sdwa v13, v90 dst_sel:DWORD dst_unused:UNUSED_PAD src0_sel:WORD_1
	v_mul_f32_e32 v11, v6, v11
	v_fma_f32 v11, v7, v12, v11
	v_fma_f32 v11, v8, v13, v11
	v_cvt_pk_bf16_f32 v82, v10, v11
	v_cvt_f32_f16_e32 v10, v87
	v_cvt_f32_f16_e32 v11, v83
	v_cvt_f32_f16_e32 v12, v91
	v_mul_f32_e32 v10, v7, v10
	v_fma_f32 v10, v6, v11, v10
	v_fma_f32 v10, v8, v12, v10
	v_cvt_f32_f16_sdwa v11, v83 dst_sel:DWORD dst_unused:UNUSED_PAD src0_sel:WORD_1
	v_cvt_f32_f16_sdwa v12, v87 dst_sel:DWORD dst_unused:UNUSED_PAD src0_sel:WORD_1
	v_cvt_f32_f16_sdwa v13, v91 dst_sel:DWORD dst_unused:UNUSED_PAD src0_sel:WORD_1
	v_mul_f32_e32 v11, v6, v11
	v_fma_f32 v11, v7, v12, v11
	v_fma_f32 v11, v8, v13, v11
	v_cvt_pk_bf16_f32 v83, v10, v11
	global_store_dwordx4 v[92:93], v[80:83], off
	s_branch .LBB0_331
